# v6 + ResNorm epilogue stage 1: residual base loads of 2 row groups in flight (was 1), row offset defs moved after stage 1
# baseline (speedup 1.0000x reference)
.LBB0_359:
	s_ashr_i32 s34, s30, 4
	v_lshl_add_u32 v178, s30, 8, v211
	v_mad_i64_i32 v[130:131], s[14:15], s34, v221, v[156:157]
	v_ashrrev_i32_e32 v179, 31, v178
	global_load_dwordx4 v[132:135], v[130:131], off
	global_load_dwordx4 v[136:139], v[130:131], off offset:16
	global_load_dwordx4 v[180:183], v[130:131], off offset:528
	global_load_dwordx4 v[184:187], v[130:131], off offset:512
	v_lshlrev_b64 v[130:131], 13, v[178:179]
	v_lshl_add_u64 v[140:141], v[158:159], 0, v[130:131]
	global_load_dwordx4 v[188:191], v[140:141], off
	global_load_dwordx4 v[200:203], v[140:141], off offset:16
	global_load_dwordx4 v[204:207], v[140:141], off offset:512
	global_load_dwordx4 v[224:227], v[140:141], off offset:528
	v_and_b32_e32 v141, 64, v216
	v_xor_b32_e32 v140, 16, v216
	v_add_u32_e32 v192, 64, v141
	v_cmp_lt_i32_e32 vcc, v140, v192
	v_readfirstlane_b32 s3, v0
	v_add_u32_e32 v240, 16, v178
	v_lshlrev_b32_e32 v240, 13, v240
	v_mov_b32_e32 v241, 0
	v_lshl_add_u64 v[240:241], v[158:159], 0, v[240:241]
	global_load_dwordx4 v[228:231], v[240:241], off
	global_load_dwordx4 v[232:235], v[240:241], off offset:16
	global_load_dwordx4 v[236:239], v[240:241], off offset:512
	s_nop 0
	global_load_dwordx4 v[240:243], v[240:241], off offset:528
	s_waitcnt vmcnt(4)
	v_pk_mul_f32 v[194:195], v[134:135], 0.5 op_sel_hi:[1,0]
	v_cndmask_b32_e32 v140, v216, v140, vcc
	v_pk_mul_f32 v[198:199], v[132:133], 0.5 op_sel_hi:[1,0]
	v_pk_mul_f32 v[144:145], v[138:139], 0.5 op_sel_hi:[1,0]
	v_pk_mul_f32 v[196:197], v[136:137], 0.5 op_sel_hi:[1,0]
	v_lshlrev_b32_e32 v223, 2, v140
	v_pk_mul_f32 v[140:141], v[186:187], 0.5 op_sel_hi:[1,0]
	v_pk_mul_f32 v[142:143], v[184:185], 0.5 op_sel_hi:[1,0]
	v_pk_fma_f32 v[88:89], v[88:89], v[194:195], v[190:191]
	v_pk_fma_f32 v[86:87], v[86:87], v[198:199], v[188:189]
	v_pk_fma_f32 v[84:85], v[84:85], v[144:145], v[202:203]
	v_pk_fma_f32 v[82:83], v[82:83], v[196:197], v[200:201]
	v_pk_mul_f32 v[136:137], v[182:183], 0.5 op_sel_hi:[1,0]
	v_pk_mul_f32 v[138:139], v[180:181], 0.5 op_sel_hi:[1,0]
	v_pk_fma_f32 v[28:29], v[28:29], v[140:141], v[206:207]
	v_pk_fma_f32 v[26:27], v[26:27], v[142:143], v[204:205]
	v_mul_f32_e32 v132, v87, v87
	v_mul_f32_e32 v133, v89, v89
	v_mul_f32_e32 v134, v83, v83
	v_mul_f32_e32 v135, v85, v85
	v_pk_fma_f32 v[32:33], v[32:33], v[136:137], v[226:227]
	v_pk_fma_f32 v[30:31], v[30:31], v[138:139], v[224:225]
	v_mul_f32_e32 v180, v27, v27
	v_mul_f32_e32 v181, v29, v29
	v_fmac_f32_e32 v132, v86, v86
	v_fmac_f32_e32 v133, v88, v88
	v_fmac_f32_e32 v134, v82, v82
	v_fmac_f32_e32 v135, v84, v84
	v_mul_f32_e32 v182, v31, v31
	v_mul_f32_e32 v183, v33, v33
	v_fmac_f32_e32 v180, v26, v26
	v_fmac_f32_e32 v181, v28, v28
	v_add_f32_e32 v132, v132, v133
	v_add_f32_e32 v133, v134, v135
	v_fmac_f32_e32 v182, v30, v30
	v_fmac_f32_e32 v183, v32, v32
	v_add_f32_e32 v134, v180, v181
	v_add_f32_e32 v132, v132, v133
	v_add_f32_e32 v132, v132, v134
	v_add_f32_e32 v133, v182, v183
	v_add_f32_e32 v132, v132, v133
	ds_bpermute_b32 v133, v223, v132
	v_xor_b32_e32 v134, 32, v216
	v_cmp_lt_i32_e32 vcc, v134, v192
	s_waitcnt lgkmcnt(0)
	v_add_f32_e32 v132, v132, v133
	v_cndmask_b32_e32 v134, v216, v134, vcc
	v_lshlrev_b32_e32 v224, 2, v134
	ds_bpermute_b32 v133, v224, v132
	s_and_saveexec_b64 s[36:37], s[4:5]
	s_cbranch_execz .LBB0_361
	s_waitcnt lgkmcnt(0)
	v_add_f32_e32 v132, v132, v133
	ds_write_b32 v222, v132
.LBB0_361:
	s_or_b64 exec, exec, s[36:37]
	s_waitcnt lgkmcnt(0)
	v_add_u32_e32 v244, 32, v178
	v_lshlrev_b32_e32 v244, 13, v244
	v_mov_b32_e32 v245, 0
	v_lshl_add_u64 v[244:245], v[158:159], 0, v[244:245]
	global_load_dwordx4 v[188:191], v[244:245], off
	global_load_dwordx4 v[200:203], v[244:245], off offset:16
	global_load_dwordx4 v[204:207], v[244:245], off offset:512
	s_nop 0
	global_load_dwordx4 v[244:247], v[244:245], off offset:528
	s_waitcnt vmcnt(4)
	v_pk_fma_f32 v[112:113], v[112:113], v[194:195], v[230:231]
	v_pk_fma_f32 v[110:111], v[110:111], v[198:199], v[228:229]
	v_pk_fma_f32 v[108:109], v[108:109], v[144:145], v[234:235]
	v_pk_fma_f32 v[106:107], v[106:107], v[196:197], v[232:233]
	v_pk_fma_f32 v[44:45], v[44:45], v[140:141], v[238:239]
	v_pk_fma_f32 v[42:43], v[42:43], v[142:143], v[236:237]
	v_mul_f32_e32 v134, v111, v111
	v_mul_f32_e32 v135, v113, v113
	v_mul_f32_e32 v182, v107, v107
	v_mul_f32_e32 v183, v109, v109
	v_pk_fma_f32 v[52:53], v[52:53], v[136:137], v[242:243]
	v_pk_fma_f32 v[50:51], v[50:51], v[138:139], v[240:241]
	v_mul_f32_e32 v184, v43, v43
	v_mul_f32_e32 v185, v45, v45
	v_fmac_f32_e32 v134, v110, v110
	v_fmac_f32_e32 v135, v112, v112
	v_fmac_f32_e32 v182, v106, v106
	v_fmac_f32_e32 v183, v108, v108
	v_mul_f32_e32 v186, v51, v51
	v_mul_f32_e32 v187, v53, v53
	v_fmac_f32_e32 v184, v42, v42
	v_fmac_f32_e32 v185, v44, v44
	v_add_f32_e32 v134, v134, v135
	v_add_f32_e32 v135, v182, v183
	v_fmac_f32_e32 v186, v50, v50
	v_fmac_f32_e32 v187, v52, v52
	v_add_f32_e32 v182, v184, v185
	v_add_f32_e32 v134, v134, v135
	v_add_f32_e32 v134, v134, v182
	v_add_f32_e32 v135, v186, v187
	v_add_f32_e32 v134, v134, v135
	ds_bpermute_b32 v135, v223, v134
	s_waitcnt lgkmcnt(0)
	v_add_f32_e32 v134, v134, v135
	ds_bpermute_b32 v135, v224, v134
	s_and_saveexec_b64 s[36:37], s[4:5]
	s_cbranch_execz .LBB0_363
	s_waitcnt lgkmcnt(0)
	v_add_f32_e32 v134, v134, v135
	ds_write_b32 v222, v134 offset:256
.LBB0_363:
	s_or_b64 exec, exec, s[36:37]
	s_waitcnt lgkmcnt(0)
	v_add_u32_e32 v230, 48, v178
	v_lshlrev_b32_e32 v230, 13, v230
	v_mov_b32_e32 v231, 0
	v_lshl_add_u64 v[230:231], v[158:159], 0, v[230:231]
	global_load_dwordx4 v[132:135], v[230:231], off
	global_load_dwordx4 v[180:183], v[230:231], off offset:16
	global_load_dwordx4 v[226:229], v[230:231], off offset:512
	s_nop 0
	global_load_dwordx4 v[230:233], v[230:231], off offset:528
	s_waitcnt vmcnt(4)
	v_pk_fma_f32 v[120:121], v[120:121], v[194:195], v[190:191]
	v_pk_fma_f32 v[118:119], v[118:119], v[198:199], v[188:189]
	v_pk_fma_f32 v[116:117], v[116:117], v[144:145], v[202:203]
	v_pk_fma_f32 v[114:115], v[114:115], v[196:197], v[200:201]
	v_pk_fma_f32 v[68:69], v[68:69], v[140:141], v[206:207]
	v_pk_fma_f32 v[66:67], v[66:67], v[142:143], v[204:205]
	v_mul_f32_e32 v184, v119, v119
	v_mul_f32_e32 v185, v121, v121
	v_mul_f32_e32 v186, v115, v115
	v_mul_f32_e32 v187, v117, v117
	v_pk_fma_f32 v[72:73], v[72:73], v[136:137], v[246:247]
	v_pk_fma_f32 v[70:71], v[70:71], v[138:139], v[244:245]
	v_mul_f32_e32 v188, v67, v67
	v_mul_f32_e32 v189, v69, v69
	v_fmac_f32_e32 v184, v118, v118
	v_fmac_f32_e32 v185, v120, v120
	v_fmac_f32_e32 v186, v114, v114
	v_fmac_f32_e32 v187, v116, v116
	v_mul_f32_e32 v190, v71, v71
	v_mul_f32_e32 v191, v73, v73
	v_fmac_f32_e32 v188, v66, v66
	v_fmac_f32_e32 v189, v68, v68
	v_add_f32_e32 v184, v184, v185
	v_add_f32_e32 v185, v186, v187
	v_fmac_f32_e32 v190, v70, v70
	v_fmac_f32_e32 v191, v72, v72
	v_add_f32_e32 v186, v188, v189
	v_add_f32_e32 v184, v184, v185
	v_add_f32_e32 v184, v184, v186
	v_add_f32_e32 v185, v190, v191
	v_add_f32_e32 v184, v184, v185
	ds_bpermute_b32 v185, v223, v184
	s_waitcnt lgkmcnt(0)
	v_add_f32_e32 v184, v184, v185
	ds_bpermute_b32 v185, v224, v184
	s_and_saveexec_b64 s[36:37], s[4:5]
	s_cbranch_execz .LBB0_365
	s_waitcnt lgkmcnt(0)
	v_add_f32_e32 v184, v184, v185
	ds_write_b32 v222, v184 offset:512
.LBB0_365:
	s_or_b64 exec, exec, s[36:37]
	s_waitcnt lgkmcnt(0)
	v_add_u32_e32 v238, 0x80, v178
	v_lshlrev_b32_e32 v238, 13, v238
	v_mov_b32_e32 v239, 0
	v_lshl_add_u64 v[238:239], v[158:159], 0, v[238:239]
	global_load_dwordx4 v[200:203], v[238:239], off
	global_load_dwordx4 v[204:207], v[238:239], off offset:16
	global_load_dwordx4 v[234:237], v[238:239], off offset:512
	s_nop 0
	global_load_dwordx4 v[238:241], v[238:239], off offset:528
	s_waitcnt vmcnt(4)
	v_pk_fma_f32 v[128:129], v[128:129], v[194:195], v[134:135]
	v_pk_fma_f32 v[126:127], v[126:127], v[198:199], v[132:133]
	v_pk_fma_f32 v[124:125], v[124:125], v[144:145], v[182:183]
	v_pk_fma_f32 v[122:123], v[122:123], v[196:197], v[180:181]
	v_pk_fma_f32 v[92:93], v[92:93], v[140:141], v[228:229]
	v_pk_fma_f32 v[90:91], v[90:91], v[142:143], v[226:227]
	v_mul_f32_e32 v186, v127, v127
	v_mul_f32_e32 v187, v129, v129
	v_mul_f32_e32 v188, v123, v123
	v_mul_f32_e32 v189, v125, v125
	v_pk_fma_f32 v[96:97], v[96:97], v[136:137], v[232:233]
	v_pk_fma_f32 v[94:95], v[94:95], v[138:139], v[230:231]
	v_mul_f32_e32 v190, v91, v91
	v_mul_f32_e32 v191, v93, v93
	v_fmac_f32_e32 v186, v126, v126
	v_fmac_f32_e32 v187, v128, v128
	v_fmac_f32_e32 v188, v122, v122
	v_fmac_f32_e32 v189, v124, v124
	v_mul_f32_e32 v192, v95, v95
	v_mul_f32_e32 v193, v97, v97
	v_fmac_f32_e32 v190, v90, v90
	v_fmac_f32_e32 v191, v92, v92
	v_add_f32_e32 v186, v186, v187
	v_add_f32_e32 v187, v188, v189
	v_fmac_f32_e32 v192, v94, v94
	v_fmac_f32_e32 v193, v96, v96
	v_add_f32_e32 v188, v190, v191
	v_add_f32_e32 v186, v186, v187
	v_add_f32_e32 v186, v186, v188
	v_add_f32_e32 v187, v192, v193
	v_add_f32_e32 v186, v186, v187
	ds_bpermute_b32 v187, v223, v186
	s_waitcnt lgkmcnt(0)
	v_add_f32_e32 v186, v186, v187
	ds_bpermute_b32 v187, v224, v186
	s_and_saveexec_b64 s[36:37], s[4:5]
	s_cbranch_execz .LBB0_367
	s_waitcnt lgkmcnt(0)
	v_add_f32_e32 v186, v186, v187
	ds_write_b32 v222, v186 offset:768
.LBB0_367:
	s_or_b64 exec, exec, s[36:37]
	s_waitcnt lgkmcnt(0)
	v_add_u32_e32 v226, 0x90, v178
	v_lshlrev_b32_e32 v226, 13, v226
	v_mov_b32_e32 v227, 0
	v_lshl_add_u64 v[226:227], v[158:159], 0, v[226:227]
	global_load_dwordx4 v[132:135], v[226:227], off
	global_load_dwordx4 v[180:183], v[226:227], off offset:16
	global_load_dwordx4 v[184:187], v[226:227], off offset:512
	s_nop 0
	global_load_dwordx4 v[226:229], v[226:227], off offset:528
	v_add_u32_e32 v250, 0xa0, v178
	v_lshlrev_b32_e32 v250, 13, v250
	v_mov_b32_e32 v251, 0
	v_lshl_add_u64 v[250:251], v[158:159], 0, v[250:251]
	global_load_dwordx4 v[230:233], v[250:251], off
	global_load_dwordx4 v[242:245], v[250:251], off offset:16
	global_load_dwordx4 v[246:249], v[250:251], off offset:512
	s_nop 0
	global_load_dwordx4 v[250:253], v[250:251], off offset:528
	s_waitcnt vmcnt(8)
	v_pk_fma_f32 v[104:105], v[104:105], v[194:195], v[202:203]
	v_pk_fma_f32 v[102:103], v[102:103], v[198:199], v[200:201]
	v_pk_fma_f32 v[100:101], v[100:101], v[144:145], v[206:207]
	v_pk_fma_f32 v[98:99], v[98:99], v[196:197], v[204:205]
	v_pk_fma_f32 v[80:81], v[80:81], v[140:141], v[236:237]
	v_pk_fma_f32 v[78:79], v[78:79], v[142:143], v[234:235]
	v_mul_f32_e32 v188, v103, v103
	v_mul_f32_e32 v189, v105, v105
	v_mul_f32_e32 v190, v99, v99
	v_mul_f32_e32 v191, v101, v101
	v_pk_fma_f32 v[76:77], v[76:77], v[136:137], v[240:241]
	v_pk_fma_f32 v[74:75], v[74:75], v[138:139], v[238:239]
	v_mul_f32_e32 v192, v79, v79
	v_mul_f32_e32 v193, v81, v81
	v_fmac_f32_e32 v188, v102, v102
	v_fmac_f32_e32 v189, v104, v104
	v_fmac_f32_e32 v190, v98, v98
	v_fmac_f32_e32 v191, v100, v100
	v_mul_f32_e32 v204, v75, v75
	v_mul_f32_e32 v205, v77, v77
	v_fmac_f32_e32 v192, v78, v78
	v_fmac_f32_e32 v193, v80, v80
	v_add_f32_e32 v188, v188, v189
	v_add_f32_e32 v189, v190, v191
	v_fmac_f32_e32 v204, v74, v74
	v_fmac_f32_e32 v205, v76, v76
	v_add_f32_e32 v190, v192, v193
	v_add_f32_e32 v188, v188, v189
	v_add_f32_e32 v188, v188, v190
	v_add_f32_e32 v189, v204, v205
	v_add_f32_e32 v188, v188, v189
	ds_bpermute_b32 v189, v223, v188
	s_waitcnt lgkmcnt(0)
	v_add_f32_e32 v188, v188, v189
	ds_bpermute_b32 v189, v224, v188
	s_and_saveexec_b64 s[36:37], s[4:5]
	s_cbranch_execz .LBB0_369
	s_waitcnt lgkmcnt(0)
	v_add_f32_e32 v188, v188, v189
	ds_write_b32 v222, v188 offset:2048
.LBB0_369:
	s_or_b64 exec, exec, s[36:37]
	s_waitcnt lgkmcnt(0)
	s_waitcnt vmcnt(4)
	v_pk_fma_f32 v[64:65], v[64:65], v[194:195], v[134:135]
	v_pk_fma_f32 v[62:63], v[62:63], v[198:199], v[132:133]
	v_pk_fma_f32 v[60:61], v[60:61], v[144:145], v[182:183]
	v_pk_fma_f32 v[58:59], v[58:59], v[196:197], v[180:181]
	v_pk_fma_f32 v[56:57], v[56:57], v[140:141], v[186:187]
	v_pk_fma_f32 v[54:55], v[54:55], v[142:143], v[184:185]
	v_mul_f32_e32 v190, v63, v63
	v_mul_f32_e32 v191, v65, v65
	v_mul_f32_e32 v192, v59, v59
	v_mul_f32_e32 v193, v61, v61
	v_pk_fma_f32 v[48:49], v[48:49], v[136:137], v[228:229]
	v_pk_fma_f32 v[46:47], v[46:47], v[138:139], v[226:227]
	v_mul_f32_e32 v206, v55, v55
	v_mul_f32_e32 v207, v57, v57
	v_fmac_f32_e32 v190, v62, v62
	v_fmac_f32_e32 v191, v64, v64
	v_fmac_f32_e32 v192, v58, v58
	v_fmac_f32_e32 v193, v60, v60
	v_mul_f32_e32 v208, v47, v47
	v_mul_f32_e32 v209, v49, v49
	v_fmac_f32_e32 v206, v54, v54
	v_fmac_f32_e32 v207, v56, v56
	v_add_f32_e32 v190, v190, v191
	v_add_f32_e32 v191, v192, v193
	v_fmac_f32_e32 v208, v46, v46
	v_fmac_f32_e32 v209, v48, v48
	v_add_f32_e32 v192, v206, v207
	v_add_f32_e32 v190, v190, v191
	v_add_f32_e32 v190, v190, v192
	v_add_f32_e32 v191, v208, v209
	v_add_f32_e32 v190, v190, v191
	ds_bpermute_b32 v191, v223, v190
	s_waitcnt lgkmcnt(0)
	v_add_f32_e32 v190, v190, v191
	ds_bpermute_b32 v191, v224, v190
	s_and_saveexec_b64 s[36:37], s[4:5]
	s_cbranch_execz .LBB0_371
	s_waitcnt lgkmcnt(0)
	v_add_f32_e32 v190, v190, v191
	ds_write_b32 v222, v190 offset:2304
.LBB0_371:
	s_or_b64 exec, exec, s[36:37]
	s_waitcnt lgkmcnt(0)
	v_add_u32_e32 v188, 0xb0, v178
	v_lshlrev_b32_e32 v188, 13, v188
	v_mov_b32_e32 v189, 0
	v_lshl_add_u64 v[188:189], v[158:159], 0, v[188:189]
	global_load_dwordx4 v[132:135], v[188:189], off
	global_load_dwordx4 v[180:183], v[188:189], off offset:16
	global_load_dwordx4 v[184:187], v[188:189], off offset:512
	s_nop 0
	global_load_dwordx4 v[188:191], v[188:189], off offset:528
	s_waitcnt vmcnt(4)
	v_pk_fma_f32 v[40:41], v[40:41], v[194:195], v[232:233]
	v_pk_fma_f32 v[38:39], v[38:39], v[198:199], v[230:231]
	v_pk_fma_f32 v[36:37], v[36:37], v[144:145], v[244:245]
	v_pk_fma_f32 v[34:35], v[34:35], v[196:197], v[242:243]
	v_pk_fma_f32 v[24:25], v[24:25], v[140:141], v[248:249]
	v_pk_fma_f32 v[22:23], v[22:23], v[142:143], v[246:247]
	v_mul_f32_e32 v192, v39, v39
	v_mul_f32_e32 v193, v41, v41
	v_mul_f32_e32 v208, v35, v35
	v_mul_f32_e32 v209, v37, v37
	v_pk_fma_f32 v[20:21], v[20:21], v[136:137], v[252:253]
	v_pk_fma_f32 v[18:19], v[18:19], v[138:139], v[250:251]
	v_mul_f32_e32 v225, v23, v23
	v_mul_f32_e32 v226, v25, v25
	v_fmac_f32_e32 v192, v38, v38
	v_fmac_f32_e32 v193, v40, v40
	v_fmac_f32_e32 v208, v34, v34
	v_fmac_f32_e32 v209, v36, v36
	v_mul_f32_e32 v227, v19, v19
	v_mul_f32_e32 v228, v21, v21
	v_fmac_f32_e32 v225, v22, v22
	v_fmac_f32_e32 v226, v24, v24
	v_add_f32_e32 v192, v192, v193
	v_add_f32_e32 v193, v208, v209
	v_fmac_f32_e32 v227, v18, v18
	v_fmac_f32_e32 v228, v20, v20
	v_add_f32_e32 v208, v225, v226
	v_add_f32_e32 v192, v192, v193
	v_add_f32_e32 v192, v192, v208
	v_add_f32_e32 v193, v227, v228
	v_add_f32_e32 v192, v192, v193
	ds_bpermute_b32 v193, v223, v192
	s_waitcnt lgkmcnt(0)
	v_add_f32_e32 v192, v192, v193
	ds_bpermute_b32 v193, v224, v192
	s_and_saveexec_b64 s[36:37], s[4:5]
	s_cbranch_execz .LBB0_373
	s_waitcnt lgkmcnt(0)
	v_add_f32_e32 v192, v192, v193
	ds_write_b32 v222, v192 offset:2560
.LBB0_373:
	s_or_b64 exec, exec, s[36:37]
	s_waitcnt lgkmcnt(0)
	s_waitcnt vmcnt(0)
	v_pk_fma_f32 v[16:17], v[16:17], v[194:195], v[134:135]
	v_pk_fma_f32 v[14:15], v[14:15], v[198:199], v[132:133]
	v_pk_fma_f32 v[12:13], v[12:13], v[144:145], v[182:183]
	v_pk_fma_f32 v[10:11], v[10:11], v[196:197], v[180:181]
	v_pk_fma_f32 v[8:9], v[8:9], v[140:141], v[186:187]
	v_pk_fma_f32 v[6:7], v[6:7], v[142:143], v[184:185]
	v_pk_fma_f32 v[4:5], v[4:5], v[136:137], v[190:191]
	v_pk_fma_f32 v[2:3], v[2:3], v[138:139], v[188:189]
	v_mul_f32_e32 v136, v15, v15
	v_mul_f32_e32 v137, v17, v17
	v_mul_f32_e32 v138, v11, v11
	v_mul_f32_e32 v139, v13, v13
	v_mul_f32_e32 v140, v7, v7
	v_mul_f32_e32 v141, v9, v9
	v_fmac_f32_e32 v136, v14, v14
	v_fmac_f32_e32 v137, v16, v16
	v_fmac_f32_e32 v138, v10, v10
	v_fmac_f32_e32 v139, v12, v12
	v_mul_f32_e32 v142, v3, v3
	v_mul_f32_e32 v143, v5, v5
	v_fmac_f32_e32 v140, v6, v6
	v_fmac_f32_e32 v141, v8, v8
	v_add_f32_e32 v136, v136, v137
	v_add_f32_e32 v137, v138, v139
	v_fmac_f32_e32 v142, v2, v2
	v_fmac_f32_e32 v143, v4, v4
	v_add_f32_e32 v138, v140, v141
	v_add_f32_e32 v136, v136, v137
	v_add_f32_e32 v136, v136, v138
	v_add_f32_e32 v137, v142, v143
	v_add_f32_e32 v136, v136, v137
	ds_bpermute_b32 v137, v223, v136
	s_waitcnt lgkmcnt(0)
	v_add_f32_e32 v136, v136, v137
	ds_bpermute_b32 v137, v224, v136
	s_and_saveexec_b64 s[36:37], s[4:5]
	s_cbranch_execz .LBB0_375
	s_waitcnt lgkmcnt(0)
	v_add_f32_e32 v136, v136, v137
	ds_write_b32 v222, v136 offset:2816
.LBB0_375:
	s_or_b64 exec, exec, s[36:37]
	v_or_b32_e32 v180, 16, v178
	v_ashrrev_i32_e32 v181, 31, v180
	v_lshlrev_b64 v[132:133], 13, v[180:181]
	v_or_b32_e32 v182, 32, v178
	v_ashrrev_i32_e32 v183, 31, v182
	v_lshlrev_b64 v[134:135], 13, v[182:183]
	v_or_b32_e32 v184, 48, v178
	v_ashrrev_i32_e32 v185, 31, v184
	v_lshlrev_b64 v[200:201], 13, v[184:185]
	v_add_u32_e32 v186, 0x80, v178
	v_ashrrev_i32_e32 v187, 31, v186
	v_lshlrev_b64 v[202:203], 13, v[186:187]
	v_add_u32_e32 v188, 0x90, v178
	v_ashrrev_i32_e32 v189, 31, v188
	v_lshlrev_b64 v[204:205], 13, v[188:189]
	v_add_u32_e32 v190, 0xa0, v178
	v_ashrrev_i32_e32 v191, 31, v190
	v_lshlrev_b64 v[206:207], 13, v[190:191]
	v_add_u32_e32 v192, 0xb0, v178
	v_ashrrev_i32_e32 v193, 31, v192
	v_lshlrev_b64 v[208:209], 13, v[192:193]
	s_waitcnt lgkmcnt(0)
	s_barrier
	s_cmpk_lt_u32 s3, 0x100
	s_cselect_b64 s[36:37], -1, 0
	s_cmpk_gt_u32 s3, 0xff
	s_cbranch_scc1 .LBB0_380
	v_add_u32_e32 v136, 0, v210
	v_add_u32_e32 v136, 0x20000, v136
	s_waitcnt lgkmcnt(0)
	ds_read_b128 v[136:139], v136
	s_ashr_i32 s31, s30, 31
	s_lshl_b64 s[14:15], s[30:31], 10
	v_lshl_add_u64 v[140:141], v[160:161], 0, s[14:15]
	s_waitcnt lgkmcnt(0)
	v_mov_b32_e32 v142, v137
	v_mov_b32_e32 v143, v138
	v_mov_b32_e32 v137, v139
	v_pk_add_f32 v[136:137], v[142:143], v[136:137]
	s_nop 0
	v_pk_add_f32 v[136:137], v[136:137], v[136:137] op_sel:[0,1] op_sel_hi:[1,0]
	global_store_dword v[140:141], v136, off sc1
	s_waitcnt vmcnt(0)
	s_and_saveexec_b64 s[38:39], s[6:7]
	s_cbranch_execz .LBB0_379
	s_mov_b64 s[40:41], exec
	v_mbcnt_lo_u32_b32 v136, s40, 0
	v_mbcnt_hi_u32_b32 v136, s41, v136
	v_cmp_eq_u32_e32 vcc, 0, v136
	s_and_b64 s[14:15], exec, vcc
	s_mov_b64 exec, s[14:15]
	s_cbranch_execz .LBB0_379
	s_lshl_b32 s14, s30, 6
	s_ashr_i32 s15, s14, 31
	s_lshl_b64 s[14:15], s[14:15], 2
	s_add_u32 s14, s56, s14
	s_addc_u32 s15, s57, s15
	s_bcnt1_i32_b64 s16, s[40:41]
	v_mov_b32_e32 v136, s16
	global_atomic_add v151, v136, s[14:15]

.LBB0_702:
	v_lshl_add_u32 v178, s36, 8, v211
	v_ashrrev_i32_e32 v179, 31, v178
	s_ashr_i32 s38, s36, 4
	v_lshlrev_b64 v[186:187], 13, v[178:179]
	v_mad_i64_i32 v[138:139], s[14:15], s38, v221, v[156:157]
	v_lshl_add_u64 v[184:185], v[158:159], 0, v[186:187]
	global_load_dwordx4 v[180:183], v[184:185], off
	global_load_dwordx4 v[134:137], v[138:139], off
	global_load_dwordx4 v[130:133], v[138:139], off offset:16
	global_load_dwordx4 v[188:191], v[184:185], off offset:16
	global_load_dwordx4 v[192:195], v[184:185], off offset:512
	global_load_dwordx4 v[142:145], v[138:139], off offset:512
	s_nop 0
	global_load_dwordx4 v[138:141], v[138:139], off offset:528
	s_nop 0
	global_load_dwordx4 v[196:199], v[184:185], off offset:528
	v_and_b32_e32 v185, 64, v217
	v_xor_b32_e32 v184, 16, v217
	v_add_u32_e32 v185, 64, v185
	v_cmp_lt_i32_e32 vcc, v184, v185
	v_readfirstlane_b32 s3, v0
	v_add_u32_e32 v230, 16, v178
	v_lshlrev_b32_e32 v230, 13, v230
	v_mov_b32_e32 v231, 0
	v_lshl_add_u64 v[230:231], v[158:159], 0, v[230:231]
	global_load_dwordx4 v[200:203], v[230:231], off
	global_load_dwordx4 v[204:207], v[230:231], off offset:16
	global_load_dwordx4 v[226:229], v[230:231], off offset:512
	s_nop 0
	global_load_dwordx4 v[230:233], v[230:231], off offset:528
	v_add_u32_e32 v246, 32, v178
	v_lshlrev_b32_e32 v246, 13, v246
	v_mov_b32_e32 v247, 0
	v_lshl_add_u64 v[246:247], v[158:159], 0, v[246:247]
	global_load_dwordx4 v[234:237], v[246:247], off
	global_load_dwordx4 v[238:241], v[246:247], off offset:16
	global_load_dwordx4 v[242:245], v[246:247], off offset:512
	s_nop 0
	global_load_dwordx4 v[246:249], v[246:247], off offset:528
	s_waitcnt vmcnt(8)
	v_pk_fma_f32 v[84:85], v[84:85], v[136:137], v[182:183]
	v_pk_fma_f32 v[82:83], v[82:83], v[134:135], v[180:181]
	v_pk_fma_f32 v[80:81], v[80:81], v[132:133], v[190:191]
	v_pk_fma_f32 v[78:79], v[78:79], v[130:131], v[188:189]
	v_cndmask_b32_e32 v184, v217, v184, vcc
	v_pk_fma_f32 v[24:25], v[24:25], v[144:145], v[194:195]
	v_pk_fma_f32 v[22:23], v[22:23], v[142:143], v[192:193]
	v_mul_f32_e32 v180, v83, v83
	v_mul_f32_e32 v181, v85, v85
	v_mul_f32_e32 v182, v79, v79
	v_mul_f32_e32 v183, v81, v81
	v_lshlrev_b32_e32 v223, 2, v184
	v_pk_fma_f32 v[28:29], v[28:29], v[140:141], v[198:199]
	v_pk_fma_f32 v[26:27], v[26:27], v[138:139], v[196:197]
	v_mul_f32_e32 v184, v23, v23
	v_mul_f32_e32 v188, v25, v25
	v_fmac_f32_e32 v180, v82, v82
	v_fmac_f32_e32 v181, v84, v84
	v_fmac_f32_e32 v182, v78, v78
	v_fmac_f32_e32 v183, v80, v80
	v_mul_f32_e32 v189, v27, v27
	v_mul_f32_e32 v190, v29, v29
	v_fmac_f32_e32 v184, v22, v22
	v_fmac_f32_e32 v188, v24, v24
	v_add_f32_e32 v180, v180, v181
	v_add_f32_e32 v181, v182, v183
	v_fmac_f32_e32 v189, v26, v26
	v_fmac_f32_e32 v190, v28, v28
	v_add_f32_e32 v182, v184, v188
	v_add_f32_e32 v180, v180, v181
	v_add_f32_e32 v180, v180, v182
	v_add_f32_e32 v181, v189, v190
	v_add_f32_e32 v180, v180, v181
	ds_bpermute_b32 v181, v223, v180
	v_xor_b32_e32 v182, 32, v217
	v_cmp_lt_i32_e32 vcc, v182, v185
	s_waitcnt lgkmcnt(0)
	v_add_f32_e32 v180, v180, v181
	v_cndmask_b32_e32 v182, v217, v182, vcc
	v_lshlrev_b32_e32 v224, 2, v182
	ds_bpermute_b32 v181, v224, v180
	s_and_saveexec_b64 s[40:41], s[4:5]
	s_cbranch_execz .LBB0_704
	s_waitcnt lgkmcnt(0)
	v_add_f32_e32 v180, v180, v181
	ds_write_b32 v222, v180
.LBB0_704:
	s_or_b64 exec, exec, s[40:41]
	s_waitcnt lgkmcnt(0)
	s_waitcnt vmcnt(4)
	v_pk_fma_f32 v[112:113], v[112:113], v[136:137], v[202:203]
	v_pk_fma_f32 v[110:111], v[110:111], v[134:135], v[200:201]
	v_pk_fma_f32 v[108:109], v[108:109], v[132:133], v[206:207]
	v_pk_fma_f32 v[106:107], v[106:107], v[130:131], v[204:205]
	v_pk_fma_f32 v[44:45], v[44:45], v[144:145], v[228:229]
	v_pk_fma_f32 v[42:43], v[42:43], v[142:143], v[226:227]
	v_mul_f32_e32 v182, v111, v111
	v_mul_f32_e32 v183, v113, v113
	v_mul_f32_e32 v184, v107, v107
	v_mul_f32_e32 v185, v109, v109
	v_pk_fma_f32 v[48:49], v[48:49], v[140:141], v[232:233]
	v_pk_fma_f32 v[46:47], v[46:47], v[138:139], v[230:231]
	v_mul_f32_e32 v188, v43, v43
	v_mul_f32_e32 v189, v45, v45
	v_fmac_f32_e32 v182, v110, v110
	v_fmac_f32_e32 v183, v112, v112
	v_fmac_f32_e32 v184, v106, v106
	v_fmac_f32_e32 v185, v108, v108
	v_mul_f32_e32 v190, v47, v47
	v_mul_f32_e32 v191, v49, v49
	v_fmac_f32_e32 v188, v42, v42
	v_fmac_f32_e32 v189, v44, v44
	v_add_f32_e32 v182, v182, v183
	v_add_f32_e32 v183, v184, v185
	v_fmac_f32_e32 v190, v46, v46
	v_fmac_f32_e32 v191, v48, v48
	v_add_f32_e32 v184, v188, v189
	v_add_f32_e32 v182, v182, v183
	v_add_f32_e32 v182, v182, v184
	v_add_f32_e32 v183, v190, v191
	v_add_f32_e32 v182, v182, v183
	ds_bpermute_b32 v183, v223, v182
	s_waitcnt lgkmcnt(0)
	v_add_f32_e32 v182, v182, v183
	ds_bpermute_b32 v183, v224, v182
	s_and_saveexec_b64 s[40:41], s[4:5]
	s_cbranch_execz .LBB0_706
	s_waitcnt lgkmcnt(0)
	v_add_f32_e32 v182, v182, v183
	ds_write_b32 v222, v182 offset:256
.LBB0_706:
	s_or_b64 exec, exec, s[40:41]
	s_waitcnt lgkmcnt(0)
	v_add_u32_e32 v204, 48, v178
	v_lshlrev_b32_e32 v204, 13, v204
	v_mov_b32_e32 v205, 0
	v_lshl_add_u64 v[204:205], v[158:159], 0, v[204:205]
	global_load_dwordx4 v[180:183], v[204:205], off
	global_load_dwordx4 v[196:199], v[204:205], off offset:16
	global_load_dwordx4 v[200:203], v[204:205], off offset:512
	s_nop 0
	global_load_dwordx4 v[204:207], v[204:205], off offset:528
	s_waitcnt vmcnt(4)
	v_pk_fma_f32 v[120:121], v[120:121], v[136:137], v[236:237]
	v_pk_fma_f32 v[118:119], v[118:119], v[134:135], v[234:235]
	v_pk_fma_f32 v[116:117], v[116:117], v[132:133], v[240:241]
	v_pk_fma_f32 v[114:115], v[114:115], v[130:131], v[238:239]
	v_pk_fma_f32 v[64:65], v[64:65], v[144:145], v[244:245]
	v_pk_fma_f32 v[62:63], v[62:63], v[142:143], v[242:243]
	v_mul_f32_e32 v184, v119, v119
	v_mul_f32_e32 v185, v121, v121
	v_mul_f32_e32 v188, v115, v115
	v_mul_f32_e32 v189, v117, v117
	v_pk_fma_f32 v[72:73], v[72:73], v[140:141], v[248:249]
	v_pk_fma_f32 v[70:71], v[70:71], v[138:139], v[246:247]
	v_mul_f32_e32 v190, v63, v63
	v_mul_f32_e32 v191, v65, v65
	v_fmac_f32_e32 v184, v118, v118
	v_fmac_f32_e32 v185, v120, v120
	v_fmac_f32_e32 v188, v114, v114
	v_fmac_f32_e32 v189, v116, v116
	v_mul_f32_e32 v194, v71, v71
	v_mul_f32_e32 v195, v73, v73
	v_fmac_f32_e32 v190, v62, v62
	v_fmac_f32_e32 v191, v64, v64
	v_add_f32_e32 v184, v184, v185
	v_add_f32_e32 v185, v188, v189
	v_fmac_f32_e32 v194, v70, v70
	v_fmac_f32_e32 v195, v72, v72
	v_add_f32_e32 v188, v190, v191
	v_add_f32_e32 v184, v184, v185
	v_add_f32_e32 v184, v184, v188
	v_add_f32_e32 v185, v194, v195
	v_add_f32_e32 v184, v184, v185
	ds_bpermute_b32 v185, v223, v184
	s_waitcnt lgkmcnt(0)
	v_add_f32_e32 v184, v184, v185
	ds_bpermute_b32 v185, v224, v184
	s_and_saveexec_b64 s[40:41], s[4:5]
	s_cbranch_execz .LBB0_708
	s_waitcnt lgkmcnt(0)
	v_add_f32_e32 v184, v184, v185
	ds_write_b32 v222, v184 offset:512
.LBB0_708:
	s_or_b64 exec, exec, s[40:41]
	s_waitcnt lgkmcnt(0)
	v_add_u32_e32 v238, 0x80, v178
	v_lshlrev_b32_e32 v238, 13, v238
	v_mov_b32_e32 v239, 0
	v_lshl_add_u64 v[238:239], v[158:159], 0, v[238:239]
	global_load_dwordx4 v[226:229], v[238:239], off
	global_load_dwordx4 v[230:233], v[238:239], off offset:16
	global_load_dwordx4 v[234:237], v[238:239], off offset:512
	s_nop 0
	global_load_dwordx4 v[238:241], v[238:239], off offset:528
	s_waitcnt vmcnt(4)
	v_pk_fma_f32 v[128:129], v[128:129], v[136:137], v[182:183]
	v_pk_fma_f32 v[126:127], v[126:127], v[134:135], v[180:181]
	v_pk_fma_f32 v[124:125], v[124:125], v[132:133], v[198:199]
	v_pk_fma_f32 v[122:123], v[122:123], v[130:131], v[196:197]
	v_pk_fma_f32 v[92:93], v[92:93], v[144:145], v[202:203]
	v_pk_fma_f32 v[90:91], v[90:91], v[142:143], v[200:201]
	v_mul_f32_e32 v188, v127, v127
	v_mul_f32_e32 v189, v129, v129
	v_mul_f32_e32 v190, v123, v123
	v_mul_f32_e32 v191, v125, v125
	v_pk_fma_f32 v[96:97], v[96:97], v[140:141], v[206:207]
	v_pk_fma_f32 v[94:95], v[94:95], v[138:139], v[204:205]
	v_mul_f32_e32 v194, v91, v91
	v_mul_f32_e32 v195, v93, v93
	v_fmac_f32_e32 v188, v126, v126
	v_fmac_f32_e32 v189, v128, v128
	v_fmac_f32_e32 v190, v122, v122
	v_fmac_f32_e32 v191, v124, v124
	v_mul_f32_e32 v198, v95, v95
	v_mul_f32_e32 v199, v97, v97
	v_fmac_f32_e32 v194, v90, v90
	v_fmac_f32_e32 v195, v92, v92
	v_add_f32_e32 v188, v188, v189
	v_add_f32_e32 v189, v190, v191
	v_fmac_f32_e32 v198, v94, v94
	v_fmac_f32_e32 v199, v96, v96
	v_add_f32_e32 v190, v194, v195
	v_add_f32_e32 v188, v188, v189
	v_add_f32_e32 v188, v188, v190
	v_add_f32_e32 v189, v198, v199
	v_add_f32_e32 v188, v188, v189
	ds_bpermute_b32 v189, v223, v188
	s_waitcnt lgkmcnt(0)
	v_add_f32_e32 v188, v188, v189
	ds_bpermute_b32 v189, v224, v188
	s_and_saveexec_b64 s[40:41], s[4:5]
	s_cbranch_execz .LBB0_710
	s_waitcnt lgkmcnt(0)
	v_add_f32_e32 v188, v188, v189
	ds_write_b32 v222, v188 offset:768
.LBB0_710:
	s_or_b64 exec, exec, s[40:41]
	s_waitcnt lgkmcnt(0)
	v_add_u32_e32 v242, 0x90, v178
	v_lshlrev_b32_e32 v242, 13, v242
	v_mov_b32_e32 v243, 0
	v_lshl_add_u64 v[242:243], v[158:159], 0, v[242:243]
	global_load_dwordx4 v[180:183], v[242:243], off
	global_load_dwordx4 v[200:203], v[242:243], off offset:16
	global_load_dwordx4 v[206:209], v[242:243], off offset:512
	s_nop 0
	global_load_dwordx4 v[242:245], v[242:243], off offset:528
	s_waitcnt vmcnt(4)
	v_pk_fma_f32 v[104:105], v[104:105], v[136:137], v[228:229]
	v_pk_fma_f32 v[102:103], v[102:103], v[134:135], v[226:227]
	v_pk_fma_f32 v[100:101], v[100:101], v[132:133], v[232:233]
	v_pk_fma_f32 v[98:99], v[98:99], v[130:131], v[230:231]
	v_pk_fma_f32 v[88:89], v[88:89], v[144:145], v[236:237]
	v_pk_fma_f32 v[86:87], v[86:87], v[142:143], v[234:235]
	v_mul_f32_e32 v190, v103, v103
	v_mul_f32_e32 v191, v105, v105
	v_mul_f32_e32 v194, v99, v99
	v_mul_f32_e32 v195, v101, v101
	v_pk_fma_f32 v[76:77], v[76:77], v[140:141], v[240:241]
	v_pk_fma_f32 v[74:75], v[74:75], v[138:139], v[238:239]
	v_mul_f32_e32 v198, v87, v87
	v_mul_f32_e32 v199, v89, v89
	v_fmac_f32_e32 v190, v102, v102
	v_fmac_f32_e32 v191, v104, v104
	v_fmac_f32_e32 v194, v98, v98
	v_fmac_f32_e32 v195, v100, v100
	v_mul_f32_e32 v204, v75, v75
	v_mul_f32_e32 v205, v77, v77
	v_fmac_f32_e32 v198, v86, v86
	v_fmac_f32_e32 v199, v88, v88
	v_add_f32_e32 v190, v190, v191
	v_add_f32_e32 v191, v194, v195
	v_fmac_f32_e32 v204, v74, v74
	v_fmac_f32_e32 v205, v76, v76
	v_add_f32_e32 v194, v198, v199
	v_add_f32_e32 v190, v190, v191
	v_add_f32_e32 v190, v190, v194
	v_add_f32_e32 v191, v204, v205
	v_add_f32_e32 v190, v190, v191
	ds_bpermute_b32 v191, v223, v190
	s_waitcnt lgkmcnt(0)
	v_add_f32_e32 v190, v190, v191
	ds_bpermute_b32 v191, v224, v190
	s_and_saveexec_b64 s[40:41], s[4:5]
	s_cbranch_execz .LBB0_712
	s_waitcnt lgkmcnt(0)
	v_add_f32_e32 v190, v190, v191
	ds_write_b32 v222, v190 offset:2048
.LBB0_712:
	s_or_b64 exec, exec, s[40:41]
	s_waitcnt lgkmcnt(0)
	v_add_u32_e32 v234, 0xa0, v178
	v_lshlrev_b32_e32 v234, 13, v234
	v_mov_b32_e32 v235, 0
	v_lshl_add_u64 v[234:235], v[158:159], 0, v[234:235]
	global_load_dwordx4 v[188:191], v[234:235], off
	global_load_dwordx4 v[226:229], v[234:235], off offset:16
	global_load_dwordx4 v[230:233], v[234:235], off offset:512
	s_nop 0
	global_load_dwordx4 v[234:237], v[234:235], off offset:528
	s_waitcnt vmcnt(4)
	v_pk_fma_f32 v[68:69], v[68:69], v[136:137], v[182:183]
	v_pk_fma_f32 v[66:67], v[66:67], v[134:135], v[180:181]
	v_pk_fma_f32 v[60:61], v[60:61], v[132:133], v[202:203]
	v_pk_fma_f32 v[58:59], v[58:59], v[130:131], v[200:201]
	v_pk_fma_f32 v[56:57], v[56:57], v[144:145], v[208:209]
	v_pk_fma_f32 v[54:55], v[54:55], v[142:143], v[206:207]
	v_mul_f32_e32 v194, v67, v67
	v_mul_f32_e32 v195, v69, v69
	v_mul_f32_e32 v198, v59, v59
	v_mul_f32_e32 v199, v61, v61
	v_pk_fma_f32 v[52:53], v[52:53], v[140:141], v[244:245]
	v_pk_fma_f32 v[50:51], v[50:51], v[138:139], v[242:243]
	v_mul_f32_e32 v206, v55, v55
	v_mul_f32_e32 v207, v57, v57
	v_fmac_f32_e32 v194, v66, v66
	v_fmac_f32_e32 v195, v68, v68
	v_fmac_f32_e32 v198, v58, v58
	v_fmac_f32_e32 v199, v60, v60
	v_mul_f32_e32 v208, v51, v51
	v_mul_f32_e32 v209, v53, v53
	v_fmac_f32_e32 v206, v54, v54
	v_fmac_f32_e32 v207, v56, v56
	v_add_f32_e32 v194, v194, v195
	v_add_f32_e32 v195, v198, v199
	v_fmac_f32_e32 v208, v50, v50
	v_fmac_f32_e32 v209, v52, v52
	v_add_f32_e32 v198, v206, v207
	v_add_f32_e32 v194, v194, v195
	v_add_f32_e32 v194, v194, v198
	v_add_f32_e32 v195, v208, v209
	v_add_f32_e32 v194, v194, v195
	ds_bpermute_b32 v195, v223, v194
	s_waitcnt lgkmcnt(0)
	v_add_f32_e32 v194, v194, v195
	ds_bpermute_b32 v195, v224, v194
	s_and_saveexec_b64 s[40:41], s[4:5]
	s_cbranch_execz .LBB0_714
	s_waitcnt lgkmcnt(0)
	v_add_f32_e32 v194, v194, v195
	ds_write_b32 v222, v194 offset:2304
.LBB0_714:
	s_or_b64 exec, exec, s[40:41]
	s_waitcnt lgkmcnt(0)
	v_add_u32_e32 v204, 0xb0, v178
	v_lshlrev_b32_e32 v204, 13, v204
	v_mov_b32_e32 v205, 0
	v_lshl_add_u64 v[204:205], v[158:159], 0, v[204:205]
	global_load_dwordx4 v[180:183], v[204:205], off
	global_load_dwordx4 v[192:195], v[204:205], off offset:16
	global_load_dwordx4 v[200:203], v[204:205], off offset:512
	s_nop 0
	global_load_dwordx4 v[204:207], v[204:205], off offset:528
	s_waitcnt vmcnt(4)
	v_pk_fma_f32 v[40:41], v[40:41], v[136:137], v[190:191]
	v_pk_fma_f32 v[38:39], v[38:39], v[134:135], v[188:189]
	v_pk_fma_f32 v[36:37], v[36:37], v[132:133], v[228:229]
	v_pk_fma_f32 v[34:35], v[34:35], v[130:131], v[226:227]
	v_pk_fma_f32 v[32:33], v[32:33], v[144:145], v[232:233]
	v_pk_fma_f32 v[30:31], v[30:31], v[142:143], v[230:231]
	v_mul_f32_e32 v198, v39, v39
	v_mul_f32_e32 v199, v41, v41
	v_mul_f32_e32 v208, v35, v35
	v_mul_f32_e32 v209, v37, v37
	v_pk_fma_f32 v[20:21], v[20:21], v[140:141], v[236:237]
	v_pk_fma_f32 v[18:19], v[18:19], v[138:139], v[234:235]
	v_mul_f32_e32 v225, v31, v31
	v_mul_f32_e32 v226, v33, v33
	v_fmac_f32_e32 v198, v38, v38
	v_fmac_f32_e32 v199, v40, v40
	v_fmac_f32_e32 v208, v34, v34
	v_fmac_f32_e32 v209, v36, v36
	v_mul_f32_e32 v227, v19, v19
	v_mul_f32_e32 v228, v21, v21
	v_fmac_f32_e32 v225, v30, v30
	v_fmac_f32_e32 v226, v32, v32
	v_add_f32_e32 v198, v198, v199
	v_add_f32_e32 v199, v208, v209
	v_fmac_f32_e32 v227, v18, v18
	v_fmac_f32_e32 v228, v20, v20
	v_add_f32_e32 v208, v225, v226
	v_add_f32_e32 v198, v198, v199
	v_add_f32_e32 v198, v198, v208
	v_add_f32_e32 v199, v227, v228
	v_add_f32_e32 v198, v198, v199
	ds_bpermute_b32 v199, v223, v198
	s_waitcnt lgkmcnt(0)
	v_add_f32_e32 v198, v198, v199
	ds_bpermute_b32 v199, v224, v198
	s_and_saveexec_b64 s[40:41], s[4:5]
	s_cbranch_execz .LBB0_716
	s_waitcnt lgkmcnt(0)
	v_add_f32_e32 v198, v198, v199
	ds_write_b32 v222, v198 offset:2560
.LBB0_716:
	s_or_b64 exec, exec, s[40:41]
	s_waitcnt lgkmcnt(0)
	s_waitcnt vmcnt(0)
	v_pk_fma_f32 v[16:17], v[16:17], v[136:137], v[182:183]
	v_pk_fma_f32 v[14:15], v[14:15], v[134:135], v[180:181]
	v_pk_fma_f32 v[12:13], v[12:13], v[132:133], v[194:195]
	v_pk_fma_f32 v[10:11], v[10:11], v[130:131], v[192:193]
	v_pk_fma_f32 v[8:9], v[8:9], v[144:145], v[202:203]
	v_pk_fma_f32 v[6:7], v[6:7], v[142:143], v[200:201]
	v_mul_f32_e32 v130, v15, v15
	v_mul_f32_e32 v131, v17, v17
	v_mul_f32_e32 v132, v11, v11
	v_mul_f32_e32 v133, v13, v13
	v_pk_fma_f32 v[4:5], v[4:5], v[140:141], v[206:207]
	v_pk_fma_f32 v[2:3], v[2:3], v[138:139], v[204:205]
	v_mul_f32_e32 v134, v7, v7
	v_mul_f32_e32 v135, v9, v9
	v_fmac_f32_e32 v130, v14, v14
	v_fmac_f32_e32 v131, v16, v16
	v_fmac_f32_e32 v132, v10, v10
	v_fmac_f32_e32 v133, v12, v12
	v_mul_f32_e32 v136, v3, v3
	v_mul_f32_e32 v137, v5, v5
	v_fmac_f32_e32 v134, v6, v6
	v_fmac_f32_e32 v135, v8, v8
	v_add_f32_e32 v130, v130, v131
	v_add_f32_e32 v131, v132, v133
	v_fmac_f32_e32 v136, v2, v2
	v_fmac_f32_e32 v137, v4, v4
	v_add_f32_e32 v132, v134, v135
	v_add_f32_e32 v130, v130, v131
	v_add_f32_e32 v130, v130, v132
	v_add_f32_e32 v131, v136, v137
	v_add_f32_e32 v130, v130, v131
	ds_bpermute_b32 v131, v223, v130
	s_waitcnt lgkmcnt(0)
	v_add_f32_e32 v130, v130, v131
	ds_bpermute_b32 v131, v224, v130
	s_and_saveexec_b64 s[40:41], s[4:5]
	s_cbranch_execz .LBB0_718
	s_waitcnt lgkmcnt(0)
	v_add_f32_e32 v130, v130, v131
	ds_write_b32 v222, v130 offset:2816
.LBB0_718:
	s_or_b64 exec, exec, s[40:41]
	v_or_b32_e32 v180, 16, v178
	v_ashrrev_i32_e32 v181, 31, v180
	v_lshlrev_b64 v[192:193], 13, v[180:181]
	v_or_b32_e32 v182, 32, v178
	v_ashrrev_i32_e32 v183, 31, v182
	v_lshlrev_b64 v[196:197], 13, v[182:183]
	v_or_b32_e32 v184, 48, v178
	v_ashrrev_i32_e32 v185, 31, v184
	v_lshlrev_b64 v[200:201], 13, v[184:185]
	v_add_u32_e32 v188, 0x80, v178
	v_ashrrev_i32_e32 v189, 31, v188
	v_lshlrev_b64 v[202:203], 13, v[188:189]
	v_add_u32_e32 v190, 0x90, v178
	v_ashrrev_i32_e32 v191, 31, v190
	v_lshlrev_b64 v[204:205], 13, v[190:191]
	v_add_u32_e32 v194, 0xa0, v178
	v_ashrrev_i32_e32 v195, 31, v194
	v_lshlrev_b64 v[206:207], 13, v[194:195]
	v_add_u32_e32 v198, 0xb0, v178
	v_ashrrev_i32_e32 v199, 31, v198
	v_lshlrev_b64 v[208:209], 13, v[198:199]
	s_waitcnt lgkmcnt(0)
	s_barrier
	s_cmpk_lt_u32 s3, 0x100
	s_cselect_b64 s[40:41], -1, 0
	s_cmpk_gt_u32 s3, 0xff
	s_cbranch_scc1 .LBB0_723
	v_add_u32_e32 v130, 0, v210
	v_add_u32_e32 v130, 0x20000, v130
	s_waitcnt lgkmcnt(0)
	ds_read_b128 v[130:133], v130
	s_ashr_i32 s37, s36, 31
	s_lshl_b64 s[14:15], s[36:37], 10
	v_lshl_add_u64 v[134:135], v[160:161], 0, s[14:15]
	s_waitcnt lgkmcnt(0)
	v_mov_b32_e32 v136, v131
	v_mov_b32_e32 v137, v132
	v_mov_b32_e32 v131, v133
	v_pk_add_f32 v[130:131], v[136:137], v[130:131]
	s_nop 0
	v_pk_add_f32 v[130:131], v[130:131], v[130:131] op_sel:[0,1] op_sel_hi:[1,0]
	global_store_dword v[134:135], v130, off sc1
	s_waitcnt vmcnt(0)
	s_and_saveexec_b64 s[42:43], s[6:7]
	s_cbranch_execz .LBB0_722
	s_mov_b64 s[44:45], exec
	v_mbcnt_lo_u32_b32 v130, s44, 0
	v_mbcnt_hi_u32_b32 v130, s45, v130
	v_cmp_eq_u32_e32 vcc, 0, v130
	s_and_b64 s[14:15], exec, vcc
	s_mov_b64 exec, s[14:15]
	s_cbranch_execz .LBB0_722
	s_lshl_b32 s14, s36, 6
	s_ashr_i32 s15, s14, 31
	s_lshl_b64 s[14:15], s[14:15], 2
	s_add_u32 s14, s61, s14
	s_addc_u32 s15, s62, s15
	s_bcnt1_i32_b64 s16, s[44:45]
	v_mov_b32_e32 v130, s16
	global_atomic_add v151, v130, s[14:15]

.LBB0_882:
	s_or_b64 exec, exec, s[38:39]
	s_waitcnt lgkmcnt(0)
	v_add_u32_e32 v210, 16, v184
	v_lshlrev_b32_e32 v210, 13, v210
	v_mov_b32_e32 v211, 0
	v_lshl_add_u64 v[210:211], v[158:159], 0, v[210:211]
	global_load_dwordx4 v[190:193], v[210:211], off
	global_load_dwordx4 v[194:197], v[210:211], off offset:16
	global_load_dwordx4 v[206:209], v[210:211], off offset:512
	s_nop 0
	global_load_dwordx4 v[210:213], v[210:211], off offset:528
	s_waitcnt vmcnt(0)
	v_pk_fma_f32 v[48:49], v[48:49], v[200:201], v[192:193]
	v_pk_fma_f32 v[46:47], v[46:47], v[204:205], v[190:191]
	v_pk_fma_f32 v[44:45], v[44:45], v[144:145], v[196:197]
	v_pk_fma_f32 v[42:43], v[42:43], v[202:203], v[194:195]
	v_pk_fma_f32 v[12:13], v[12:13], v[140:141], v[208:209]
	v_pk_fma_f32 v[10:11], v[10:11], v[142:143], v[206:207]
	v_mul_f32_e32 v134, v47, v47
	v_mul_f32_e32 v135, v49, v49
	v_mul_f32_e32 v188, v43, v43
	v_mul_f32_e32 v189, v45, v45
	v_pk_fma_f32 v[16:17], v[16:17], v[136:137], v[212:213]
	v_pk_fma_f32 v[14:15], v[14:15], v[138:139], v[210:211]
	v_mul_f32_e32 v190, v11, v11
	v_mul_f32_e32 v191, v13, v13
	v_fmac_f32_e32 v134, v46, v46
	v_fmac_f32_e32 v135, v48, v48
	v_fmac_f32_e32 v188, v42, v42
	v_fmac_f32_e32 v189, v44, v44
	v_mul_f32_e32 v192, v15, v15
	v_mul_f32_e32 v193, v17, v17
	v_fmac_f32_e32 v190, v10, v10
	v_fmac_f32_e32 v191, v12, v12
	v_add_f32_e32 v134, v134, v135
	v_add_f32_e32 v135, v188, v189
	v_fmac_f32_e32 v192, v14, v14
	v_fmac_f32_e32 v193, v16, v16
	v_add_f32_e32 v188, v190, v191
	v_add_f32_e32 v134, v134, v135
	v_add_f32_e32 v134, v134, v188
	v_add_f32_e32 v135, v192, v193
	v_add_f32_e32 v134, v134, v135
	ds_bpermute_b32 v135, v228, v134
	s_waitcnt lgkmcnt(0)
	v_add_f32_e32 v134, v134, v135
	ds_bpermute_b32 v135, v229, v134
	s_and_saveexec_b64 s[38:39], s[4:5]
	s_cbranch_execz .LBB0_884
	s_waitcnt lgkmcnt(0)
	v_add_f32_e32 v134, v134, v135
	ds_write_b32 v227, v134 offset:256
.LBB0_884:
	s_or_b64 exec, exec, s[38:39]
	s_waitcnt lgkmcnt(0)
	v_add_u32_e32 v206, 32, v184
	v_lshlrev_b32_e32 v206, 13, v206
	v_mov_b32_e32 v207, 0
	v_lshl_add_u64 v[206:207], v[158:159], 0, v[206:207]
	global_load_dwordx4 v[132:135], v[206:207], off
	global_load_dwordx4 v[186:189], v[206:207], off offset:16
	global_load_dwordx4 v[194:197], v[206:207], off offset:512
	s_nop 0
	global_load_dwordx4 v[206:209], v[206:207], off offset:528
	v_add_u32_e32 v250, 48, v184
	v_lshlrev_b32_e32 v250, 13, v250
	v_mov_b32_e32 v251, 0
	v_lshl_add_u64 v[250:251], v[158:159], 0, v[250:251]
	global_load_dwordx4 v[210:213], v[250:251], off
	global_load_dwordx4 v[230:233], v[250:251], off offset:16
	global_load_dwordx4 v[246:249], v[250:251], off offset:512
	s_nop 0
	global_load_dwordx4 v[250:253], v[250:251], off offset:528
	s_waitcnt vmcnt(4)
	v_pk_fma_f32 v[64:65], v[64:65], v[200:201], v[134:135]
	v_pk_fma_f32 v[62:63], v[62:63], v[204:205], v[132:133]
	v_pk_fma_f32 v[60:61], v[60:61], v[144:145], v[188:189]
	v_pk_fma_f32 v[58:59], v[58:59], v[202:203], v[186:187]
	v_pk_fma_f32 v[20:21], v[20:21], v[140:141], v[196:197]
	v_pk_fma_f32 v[18:19], v[18:19], v[142:143], v[194:195]
	v_mul_f32_e32 v190, v63, v63
	v_mul_f32_e32 v191, v65, v65
	v_mul_f32_e32 v192, v59, v59
	v_mul_f32_e32 v193, v61, v61
	v_pk_fma_f32 v[24:25], v[24:25], v[136:137], v[208:209]
	v_pk_fma_f32 v[22:23], v[22:23], v[138:139], v[206:207]
	v_mul_f32_e32 v194, v19, v19
	v_mul_f32_e32 v195, v21, v21
	v_fmac_f32_e32 v190, v62, v62
	v_fmac_f32_e32 v191, v64, v64
	v_fmac_f32_e32 v192, v58, v58
	v_fmac_f32_e32 v193, v60, v60
	v_mul_f32_e32 v196, v23, v23
	v_mul_f32_e32 v197, v25, v25
	v_fmac_f32_e32 v194, v18, v18
	v_fmac_f32_e32 v195, v20, v20
	v_add_f32_e32 v190, v190, v191
	v_add_f32_e32 v191, v192, v193
	v_fmac_f32_e32 v196, v22, v22
	v_fmac_f32_e32 v197, v24, v24
	v_add_f32_e32 v192, v194, v195
	v_add_f32_e32 v190, v190, v191
	v_add_f32_e32 v190, v190, v192
	v_add_f32_e32 v191, v196, v197
	v_add_f32_e32 v190, v190, v191
	ds_bpermute_b32 v191, v228, v190
	s_waitcnt lgkmcnt(0)
	v_add_f32_e32 v190, v190, v191
	ds_bpermute_b32 v191, v229, v190
	s_and_saveexec_b64 s[38:39], s[4:5]
	s_cbranch_execz .LBB0_886
	s_waitcnt lgkmcnt(0)
	v_add_f32_e32 v190, v190, v191
	ds_write_b32 v227, v190 offset:512
.LBB0_886:
	s_or_b64 exec, exec, s[38:39]
	s_waitcnt lgkmcnt(0)
	s_waitcnt vmcnt(0)
	v_pk_fma_f32 v[96:97], v[96:97], v[200:201], v[212:213]
	v_pk_fma_f32 v[94:95], v[94:95], v[204:205], v[210:211]
	v_pk_fma_f32 v[92:93], v[92:93], v[144:145], v[232:233]
	v_pk_fma_f32 v[90:91], v[90:91], v[202:203], v[230:231]
	v_pk_fma_f32 v[36:37], v[36:37], v[140:141], v[248:249]
	v_pk_fma_f32 v[34:35], v[34:35], v[142:143], v[246:247]
	v_mul_f32_e32 v192, v95, v95
	v_mul_f32_e32 v193, v97, v97
	v_mul_f32_e32 v194, v91, v91
	v_mul_f32_e32 v195, v93, v93
	v_pk_fma_f32 v[40:41], v[40:41], v[136:137], v[252:253]
	v_pk_fma_f32 v[38:39], v[38:39], v[138:139], v[250:251]
	v_mul_f32_e32 v196, v35, v35
	v_mul_f32_e32 v197, v37, v37
	v_fmac_f32_e32 v192, v94, v94
	v_fmac_f32_e32 v193, v96, v96
	v_fmac_f32_e32 v194, v90, v90
	v_fmac_f32_e32 v195, v92, v92
	v_mul_f32_e32 v198, v39, v39
	v_mul_f32_e32 v199, v41, v41
	v_fmac_f32_e32 v196, v34, v34
	v_fmac_f32_e32 v197, v36, v36
	v_add_f32_e32 v192, v192, v193
	v_add_f32_e32 v193, v194, v195
	v_fmac_f32_e32 v198, v38, v38
	v_fmac_f32_e32 v199, v40, v40
	v_add_f32_e32 v194, v196, v197
	v_add_f32_e32 v192, v192, v193
	v_add_f32_e32 v192, v192, v194
	v_add_f32_e32 v193, v198, v199
	v_add_f32_e32 v192, v192, v193
	ds_bpermute_b32 v193, v228, v192
	s_waitcnt lgkmcnt(0)
	v_add_f32_e32 v192, v192, v193
	ds_bpermute_b32 v193, v229, v192
	s_and_saveexec_b64 s[38:39], s[4:5]
	s_cbranch_execz .LBB0_888
	s_waitcnt lgkmcnt(0)
	v_add_f32_e32 v192, v192, v193
	ds_write_b32 v227, v192 offset:768
.LBB0_888:
	s_or_b64 exec, exec, s[38:39]
	s_waitcnt lgkmcnt(0)
	v_add_u32_e32 v206, 0x80, v184
	v_lshlrev_b32_e32 v206, 13, v206
	v_mov_b32_e32 v207, 0
	v_lshl_add_u64 v[206:207], v[158:159], 0, v[206:207]
	global_load_dwordx4 v[132:135], v[206:207], off
	global_load_dwordx4 v[186:189], v[206:207], off offset:16
	global_load_dwordx4 v[190:193], v[206:207], off offset:512
	s_nop 0
	global_load_dwordx4 v[206:209], v[206:207], off offset:528
	v_add_u32_e32 v250, 0x90, v184
	v_lshlrev_b32_e32 v250, 13, v250
	v_mov_b32_e32 v251, 0
	v_lshl_add_u64 v[250:251], v[158:159], 0, v[250:251]
	global_load_dwordx4 v[212:215], v[250:251], off
	global_load_dwordx4 v[230:233], v[250:251], off offset:16
	global_load_dwordx4 v[246:249], v[250:251], off offset:512
	s_nop 0
	global_load_dwordx4 v[250:253], v[250:251], off offset:528
	s_waitcnt vmcnt(4)
	v_pk_fma_f32 v[116:117], v[116:117], v[200:201], v[134:135]
	v_pk_fma_f32 v[114:115], v[114:115], v[204:205], v[132:133]
	v_pk_fma_f32 v[112:113], v[112:113], v[144:145], v[188:189]
	v_pk_fma_f32 v[110:111], v[110:111], v[202:203], v[186:187]
	v_pk_fma_f32 v[52:53], v[52:53], v[140:141], v[192:193]
	v_pk_fma_f32 v[50:51], v[50:51], v[142:143], v[190:191]
	v_mul_f32_e32 v194, v115, v115
	v_mul_f32_e32 v195, v117, v117
	v_mul_f32_e32 v196, v111, v111
	v_mul_f32_e32 v197, v113, v113
	v_pk_fma_f32 v[56:57], v[56:57], v[136:137], v[208:209]
	v_pk_fma_f32 v[54:55], v[54:55], v[138:139], v[206:207]
	v_mul_f32_e32 v198, v51, v51
	v_mul_f32_e32 v199, v53, v53
	v_fmac_f32_e32 v194, v114, v114
	v_fmac_f32_e32 v195, v116, v116
	v_fmac_f32_e32 v196, v110, v110
	v_fmac_f32_e32 v197, v112, v112
	v_mul_f32_e32 v210, v55, v55
	v_mul_f32_e32 v211, v57, v57
	v_fmac_f32_e32 v198, v50, v50
	v_fmac_f32_e32 v199, v52, v52
	v_add_f32_e32 v194, v194, v195
	v_add_f32_e32 v195, v196, v197
	v_fmac_f32_e32 v210, v54, v54
	v_fmac_f32_e32 v211, v56, v56
	v_add_f32_e32 v196, v198, v199
	v_add_f32_e32 v194, v194, v195
	v_add_f32_e32 v194, v194, v196
	v_add_f32_e32 v195, v210, v211
	v_add_f32_e32 v194, v194, v195
	ds_bpermute_b32 v195, v228, v194
	s_waitcnt lgkmcnt(0)
	v_add_f32_e32 v194, v194, v195
	ds_bpermute_b32 v195, v229, v194
	s_and_saveexec_b64 s[38:39], s[4:5]
	s_cbranch_execz .LBB0_890
	s_waitcnt lgkmcnt(0)
	v_add_f32_e32 v194, v194, v195
	ds_write_b32 v227, v194 offset:2048
.LBB0_890:
	s_or_b64 exec, exec, s[38:39]
	s_waitcnt lgkmcnt(0)
	v_add_u32_e32 v206, 0xa0, v184
	v_lshlrev_b32_e32 v206, 13, v206
	v_mov_b32_e32 v207, 0
	v_lshl_add_u64 v[206:207], v[158:159], 0, v[206:207]
	global_load_dwordx4 v[132:135], v[206:207], off
	global_load_dwordx4 v[186:189], v[206:207], off offset:16
	global_load_dwordx4 v[190:193], v[206:207], off offset:512
	s_nop 0
	global_load_dwordx4 v[206:209], v[206:207], off offset:528
	s_waitcnt vmcnt(4)
	v_pk_fma_f32 v[128:129], v[128:129], v[200:201], v[214:215]
	v_pk_fma_f32 v[126:127], v[126:127], v[204:205], v[212:213]
	v_pk_fma_f32 v[124:125], v[124:125], v[144:145], v[232:233]
	v_pk_fma_f32 v[122:123], v[122:123], v[202:203], v[230:231]
	v_pk_fma_f32 v[84:85], v[84:85], v[140:141], v[248:249]
	v_pk_fma_f32 v[82:83], v[82:83], v[142:143], v[246:247]
	v_mul_f32_e32 v196, v127, v127
	v_mul_f32_e32 v197, v129, v129
	v_mul_f32_e32 v198, v123, v123
	v_mul_f32_e32 v199, v125, v125
	v_pk_fma_f32 v[88:89], v[88:89], v[136:137], v[252:253]
	v_pk_fma_f32 v[86:87], v[86:87], v[138:139], v[250:251]
	v_mul_f32_e32 v212, v83, v83
	v_mul_f32_e32 v213, v85, v85
	v_fmac_f32_e32 v196, v126, v126
	v_fmac_f32_e32 v197, v128, v128
	v_fmac_f32_e32 v198, v122, v122
	v_fmac_f32_e32 v199, v124, v124
	v_mul_f32_e32 v214, v87, v87
	v_mul_f32_e32 v215, v89, v89
	v_fmac_f32_e32 v212, v82, v82
	v_fmac_f32_e32 v213, v84, v84
	v_add_f32_e32 v196, v196, v197
	v_add_f32_e32 v197, v198, v199
	v_fmac_f32_e32 v214, v86, v86
	v_fmac_f32_e32 v215, v88, v88
	v_add_f32_e32 v198, v212, v213
	v_add_f32_e32 v196, v196, v197
	v_add_f32_e32 v196, v196, v198
	v_add_f32_e32 v197, v214, v215
	v_add_f32_e32 v196, v196, v197
	ds_bpermute_b32 v197, v228, v196
	s_waitcnt lgkmcnt(0)
	v_add_f32_e32 v196, v196, v197
	ds_bpermute_b32 v197, v229, v196
	s_and_saveexec_b64 s[38:39], s[4:5]
	s_cbranch_execz .LBB0_892
	s_waitcnt lgkmcnt(0)
	v_add_f32_e32 v196, v196, v197
	ds_write_b32 v227, v196 offset:2304
.LBB0_892:
	s_or_b64 exec, exec, s[38:39]
	s_waitcnt lgkmcnt(0)
	v_add_u32_e32 v250, 0xb0, v184
	v_lshlrev_b32_e32 v250, 13, v250
	v_mov_b32_e32 v251, 0
	v_lshl_add_u64 v[250:251], v[158:159], 0, v[250:251]
	global_load_dwordx4 v[194:197], v[250:251], off
	global_load_dwordx4 v[210:213], v[250:251], off offset:16
	global_load_dwordx4 v[246:249], v[250:251], off offset:512
	s_nop 0
	global_load_dwordx4 v[250:253], v[250:251], off offset:528
	s_waitcnt vmcnt(4)
	v_pk_fma_f32 v[120:121], v[120:121], v[200:201], v[134:135]
	v_pk_fma_f32 v[118:119], v[118:119], v[204:205], v[132:133]
	v_pk_fma_f32 v[108:109], v[108:109], v[144:145], v[188:189]
	v_pk_fma_f32 v[106:107], v[106:107], v[202:203], v[186:187]
	v_pk_fma_f32 v[104:105], v[104:105], v[140:141], v[192:193]
	v_pk_fma_f32 v[102:103], v[102:103], v[142:143], v[190:191]
	v_mul_f32_e32 v198, v119, v119
	v_mul_f32_e32 v199, v121, v121
	v_mul_f32_e32 v214, v107, v107
	v_mul_f32_e32 v215, v109, v109
	v_pk_fma_f32 v[100:101], v[100:101], v[136:137], v[208:209]
	v_pk_fma_f32 v[98:99], v[98:99], v[138:139], v[206:207]
	v_mul_f32_e32 v230, v103, v103
	v_mul_f32_e32 v231, v105, v105
	v_fmac_f32_e32 v198, v118, v118
	v_fmac_f32_e32 v199, v120, v120
	v_fmac_f32_e32 v214, v106, v106
	v_fmac_f32_e32 v215, v108, v108
	v_mul_f32_e32 v232, v99, v99
	v_mul_f32_e32 v233, v101, v101
	v_fmac_f32_e32 v230, v102, v102
	v_fmac_f32_e32 v231, v104, v104
	v_add_f32_e32 v198, v198, v199
	v_add_f32_e32 v199, v214, v215
	v_fmac_f32_e32 v232, v98, v98
	v_fmac_f32_e32 v233, v100, v100
	v_add_f32_e32 v214, v230, v231
	v_add_f32_e32 v198, v198, v199
	v_add_f32_e32 v198, v198, v214
	v_add_f32_e32 v199, v232, v233
	v_add_f32_e32 v198, v198, v199
	ds_bpermute_b32 v199, v228, v198
	s_waitcnt lgkmcnt(0)
	v_add_f32_e32 v198, v198, v199
	ds_bpermute_b32 v199, v229, v198
	s_and_saveexec_b64 s[38:39], s[4:5]
	s_cbranch_execz .LBB0_894
	s_waitcnt lgkmcnt(0)
	v_add_f32_e32 v198, v198, v199
	ds_write_b32 v227, v198 offset:2560
.LBB0_894:
	s_or_b64 exec, exec, s[38:39]
	s_waitcnt lgkmcnt(0)
	s_waitcnt vmcnt(0)
	v_pk_fma_f32 v[80:81], v[80:81], v[200:201], v[196:197]
	v_pk_fma_f32 v[78:79], v[78:79], v[204:205], v[194:195]
	v_pk_fma_f32 v[76:77], v[76:77], v[144:145], v[212:213]
	v_pk_fma_f32 v[74:75], v[74:75], v[202:203], v[210:211]
	v_pk_fma_f32 v[72:73], v[72:73], v[140:141], v[248:249]
	v_pk_fma_f32 v[70:71], v[70:71], v[142:143], v[246:247]
	v_pk_fma_f32 v[68:69], v[68:69], v[136:137], v[252:253]
	v_pk_fma_f32 v[66:67], v[66:67], v[138:139], v[250:251]
	v_mul_f32_e32 v136, v79, v79
	v_mul_f32_e32 v137, v81, v81
	v_mul_f32_e32 v138, v75, v75
	v_mul_f32_e32 v139, v77, v77
	v_mul_f32_e32 v140, v71, v71
	v_mul_f32_e32 v141, v73, v73
	v_fmac_f32_e32 v136, v78, v78
	v_fmac_f32_e32 v137, v80, v80
	v_fmac_f32_e32 v138, v74, v74
	v_fmac_f32_e32 v139, v76, v76
	v_mul_f32_e32 v142, v67, v67
	v_mul_f32_e32 v143, v69, v69
	v_fmac_f32_e32 v140, v70, v70
	v_fmac_f32_e32 v141, v72, v72
	v_add_f32_e32 v136, v136, v137
	v_add_f32_e32 v137, v138, v139
	v_fmac_f32_e32 v142, v66, v66
	v_fmac_f32_e32 v143, v68, v68
	v_add_f32_e32 v138, v140, v141
	v_add_f32_e32 v136, v136, v137
	v_add_f32_e32 v136, v136, v138
	v_add_f32_e32 v137, v142, v143
	v_add_f32_e32 v136, v136, v137
	ds_bpermute_b32 v137, v228, v136
	s_waitcnt lgkmcnt(0)
	v_add_f32_e32 v136, v136, v137
	ds_bpermute_b32 v137, v229, v136
	s_and_saveexec_b64 s[38:39], s[4:5]
	s_cbranch_execz .LBB0_896
	s_waitcnt lgkmcnt(0)
	v_add_f32_e32 v136, v136, v137
	ds_write_b32 v227, v136 offset:2816
.LBB0_896:
	s_or_b64 exec, exec, s[38:39]
	v_or_b32_e32 v186, 16, v184
	v_ashrrev_i32_e32 v187, 31, v186
	v_lshlrev_b64 v[132:133], 13, v[186:187]
	v_or_b32_e32 v188, 32, v184
	v_ashrrev_i32_e32 v189, 31, v188
	v_lshlrev_b64 v[134:135], 13, v[188:189]
	v_or_b32_e32 v190, 48, v184
	v_ashrrev_i32_e32 v191, 31, v190
	v_lshlrev_b64 v[206:207], 13, v[190:191]
	v_add_u32_e32 v192, 0x80, v184
	v_ashrrev_i32_e32 v193, 31, v192
	v_lshlrev_b64 v[208:209], 13, v[192:193]
	v_add_u32_e32 v194, 0x90, v184
	v_ashrrev_i32_e32 v195, 31, v194
	v_lshlrev_b64 v[210:211], 13, v[194:195]
	v_add_u32_e32 v196, 0xa0, v184
	v_ashrrev_i32_e32 v197, 31, v196
	v_lshlrev_b64 v[212:213], 13, v[196:197]
	v_add_u32_e32 v198, 0xb0, v184
	v_ashrrev_i32_e32 v199, 31, v198
	v_lshlrev_b64 v[214:215], 13, v[198:199]
	s_waitcnt lgkmcnt(0)
	s_barrier
	s_cmpk_lt_u32 s3, 0x100
	s_cselect_b64 s[38:39], -1, 0
	s_cmpk_gt_u32 s3, 0xff
	s_cbranch_scc1 .LBB0_901
	v_add_u32_e32 v136, 0, v216
	v_add_u32_e32 v136, 0x20000, v136
	s_waitcnt lgkmcnt(0)
	ds_read_b128 v[136:139], v136
	s_ashr_i32 s35, s34, 31
	s_lshl_b64 s[14:15], s[34:35], 10
	v_lshl_add_u64 v[140:141], v[160:161], 0, s[14:15]
	s_waitcnt lgkmcnt(0)
	v_mov_b32_e32 v142, v137
	v_mov_b32_e32 v143, v138
	v_mov_b32_e32 v137, v139
	v_pk_add_f32 v[136:137], v[142:143], v[136:137]
	s_nop 0
	v_pk_add_f32 v[136:137], v[136:137], v[136:137] op_sel:[0,1] op_sel_hi:[1,0]
	global_store_dword v[140:141], v136, off sc1
	s_waitcnt vmcnt(0)
	s_and_saveexec_b64 s[40:41], s[6:7]
	s_cbranch_execz .LBB0_900
	s_mov_b64 s[42:43], exec
	v_mbcnt_lo_u32_b32 v136, s42, 0
	v_mbcnt_hi_u32_b32 v136, s43, v136
	v_cmp_eq_u32_e32 vcc, 0, v136
	s_and_b64 s[14:15], exec, vcc
	s_mov_b64 exec, s[14:15]
	s_cbranch_execz .LBB0_900
	s_lshl_b32 s14, s34, 6
	s_ashr_i32 s15, s14, 31
	s_lshl_b64 s[14:15], s[14:15], 2
	s_add_u32 s14, s66, s14
	s_addc_u32 s15, s67, s15
	s_bcnt1_i32_b64 s16, s[42:43]
	v_mov_b32_e32 v136, s16
	global_atomic_add v151, v136, s[14:15]

.LBB0_1516:
	s_or_b64 exec, exec, s[40:41]
	v_or_b32_e32 v180, 16, v178
	v_ashrrev_i32_e32 v181, 31, v180
	v_lshlrev_b64 v[192:193], 13, v[180:181]
	v_or_b32_e32 v182, 32, v178
	v_ashrrev_i32_e32 v183, 31, v182
	v_lshlrev_b64 v[196:197], 13, v[182:183]
	v_or_b32_e32 v184, 48, v178
	v_ashrrev_i32_e32 v185, 31, v184
	v_lshlrev_b64 v[200:201], 13, v[184:185]
	v_add_u32_e32 v188, 0x80, v178
	v_ashrrev_i32_e32 v189, 31, v188
	v_lshlrev_b64 v[202:203], 13, v[188:189]
	v_add_u32_e32 v190, 0x90, v178
	v_ashrrev_i32_e32 v191, 31, v190
	v_lshlrev_b64 v[204:205], 13, v[190:191]
	v_add_u32_e32 v194, 0xa0, v178
	v_ashrrev_i32_e32 v195, 31, v194
	v_lshlrev_b64 v[206:207], 13, v[194:195]
	v_add_u32_e32 v198, 0xb0, v178
	v_ashrrev_i32_e32 v199, 31, v198
	v_lshlrev_b64 v[208:209], 13, v[198:199]
	s_waitcnt lgkmcnt(0)
	s_barrier
	s_cmpk_lt_u32 s3, 0x100
	s_cselect_b64 s[40:41], -1, 0
	s_cmpk_gt_u32 s3, 0xff
	s_cbranch_scc1 .LBB0_1521
	v_add_u32_e32 v130, 0, v210
	v_add_u32_e32 v130, 0x20000, v130
	s_waitcnt lgkmcnt(0)
	ds_read_b128 v[130:133], v130
	s_ashr_i32 s37, s36, 31
	s_lshl_b64 s[14:15], s[36:37], 10
	v_lshl_add_u64 v[134:135], v[160:161], 0, s[14:15]
	s_waitcnt lgkmcnt(0)
	v_mov_b32_e32 v136, v131
	v_mov_b32_e32 v137, v132
	v_mov_b32_e32 v131, v133
	v_pk_add_f32 v[130:131], v[136:137], v[130:131]
	s_nop 0
	v_pk_add_f32 v[130:131], v[130:131], v[130:131] op_sel:[0,1] op_sel_hi:[1,0]
	global_store_dword v[134:135], v130, off sc1
	s_waitcnt vmcnt(0)
	s_and_saveexec_b64 s[42:43], s[6:7]
	s_cbranch_execz .LBB0_1520
	s_mov_b64 s[44:45], exec
	v_mbcnt_lo_u32_b32 v130, s44, 0
	v_mbcnt_hi_u32_b32 v130, s45, v130
	v_cmp_eq_u32_e32 vcc, 0, v130
	s_and_b64 s[14:15], exec, vcc
	s_mov_b64 exec, s[14:15]
	s_cbranch_execz .LBB0_1520
	s_lshl_b32 s14, s36, 6
	s_ashr_i32 s15, s14, 31
	s_lshl_b64 s[14:15], s[14:15], 2
	s_add_u32 s14, s59, s14
	s_addc_u32 s15, s60, s15
	s_bcnt1_i32_b64 s0, s[44:45]
	v_mov_b32_e32 v130, s0
	global_atomic_add v151, v130, s[14:15]
